# speedup vs baseline: 1.0061x; 1.0001x over previous
; __global__ void __launch_bounds__(512) fwd_megakernel(Args args) {
;     ...
;             float ga = 0.f, gk = 0.f, gb = 0.f, gl = 0.f, sk = 0.f, rb = 0.f;
;             for (int j = 0; j < 64; ++j) { ga = fmaxf(ga, fabsf(args.in[6][j])); gk = fmaxf(gk, fabsf(args.in[7][j])); gb = fmaxf(gb, fabsf(args.in[9][j])); gl = fmaxf(gl, fabsf(args.in[10][j])); }
;             for (int j = 0; j < 8; ++j) sk = fmaxf(sk, fabsf(args.in[8][j]));
;             for (int e = lane; e < 8 * 465; e += 64) rb = fmaxf(rb, fabsf(args.in[11][e]));
; #pragma unroll
;             for (int o = 1; o < 64; o <<= 1) rb = fmaxf(rb, __shfl_xor(rb, o));
.LBB0_363:
	s_add_u32 s2, s20, s0
	s_addc_u32 s3, s21, s1
	global_load_dwordx4 v[2:5], v0, s[2:3] offset:16
	global_load_dwordx4 v[6:9], v0, s[2:3]
	s_add_u32 s2, s22, s0
	s_addc_u32 s3, s23, s1
	global_load_dwordx4 v[16:19], v0, s[2:3]
	global_load_dwordx4 v[20:23], v0, s[2:3] offset:16
	s_add_u32 s2, s38, s0
	s_addc_u32 s3, s39, s1
	global_load_dwordx4 v[24:27], v0, s[2:3]
	global_load_dwordx4 v[28:31], v0, s[2:3] offset:16
	s_add_u32 s2, s40, s0
	s_addc_u32 s3, s41, s1
	global_load_dwordx4 v[32:35], v0, s[2:3]
	global_load_dwordx4 v[36:39], v0, s[2:3] offset:16
	s_add_u32 s0, s0, 32
	s_addc_u32 s1, s1, 0
	s_cmpk_eq_i32 s0, 0x100
	s_waitcnt vmcnt(6)
	v_max3_f32 v1, v14, |v6|, |v7|
	v_max3_f32 v1, v1, |v8|, |v9|
	s_waitcnt vmcnt(5)
	v_max3_f32 v6, v15, |v16|, |v17|
	v_max3_f32 v1, v1, |v2|, |v3|
	v_max3_f32 v2, v6, |v18|, |v19|
	v_max3_f32 v14, v1, |v4|, |v5|
	s_waitcnt vmcnt(3)
	v_max3_f32 v1, v12, |v24|, |v25|
	v_max3_f32 v2, v2, |v20|, |v21|
	v_max3_f32 v1, v1, |v26|, |v27|
	v_max3_f32 v15, v2, |v22|, |v23|
	s_waitcnt vmcnt(1)
	v_max3_f32 v2, v13, |v32|, |v33|
	v_max3_f32 v1, v1, |v28|, |v29|
	v_max3_f32 v2, v2, |v34|, |v35|
	v_max3_f32 v12, v1, |v30|, |v31|
	s_waitcnt vmcnt(0)
	v_max3_f32 v1, v2, |v36|, |v37|
	v_max3_f32 v13, v1, |v38|, |v39|
	s_cbranch_scc0 .LBB0_363
	v_mov_b32_e32 v9, 0
	global_load_dwordx4 v[0:3], v9, s[36:37] offset:16
	global_load_dwordx4 v[4:7], v9, s[36:37]
	v_sub_u32_e32 v8, 0xe87, v128
	v_lshrrev_b32_e32 v8, 6, v8
	v_add_u32_e32 v17, 1, v8
	v_or_b32_e32 v129, 64, v128
	v_and_b32_e32 v16, 62, v17
	s_mov_b32 s6, 2
	s_mov_b64 s[4:5], 0
	v_mov_b64_e32 v[10:11], v[128:129]
	v_mov_b32_e32 v20, 0
	v_mov_b32_e32 v21, 0
	v_lshlrev_b32_e32 v8, 2, v128
	v_mov_b32_e32 v10, 0
	global_load_dword v16, v8, s[42:43]
	global_load_dword v17, v8, s[42:43] offset:256
	global_load_dword v18, v8, s[42:43] offset:512
	global_load_dword v19, v8, s[42:43] offset:768
	global_load_dword v20, v8, s[42:43] offset:1024
	global_load_dword v21, v8, s[42:43] offset:1280
	global_load_dword v22, v8, s[42:43] offset:1536
	global_load_dword v23, v8, s[42:43] offset:1792
	global_load_dword v24, v8, s[42:43] offset:2048
	global_load_dword v25, v8, s[42:43] offset:2304
	global_load_dword v26, v8, s[42:43] offset:2560
	global_load_dword v27, v8, s[42:43] offset:2816
	global_load_dword v28, v8, s[42:43] offset:3072
	global_load_dword v29, v8, s[42:43] offset:3328
	global_load_dword v30, v8, s[42:43] offset:3584
	global_load_dword v31, v8, s[42:43] offset:3840
	s_waitcnt vmcnt(0)
	v_max3_f32 v10, v10, |v16|, |v17|
	v_max3_f32 v10, v10, |v18|, |v19|
	v_max3_f32 v10, v10, |v20|, |v21|
	v_max3_f32 v10, v10, |v22|, |v23|
	v_max3_f32 v10, v10, |v24|, |v25|
	v_max3_f32 v10, v10, |v26|, |v27|
	v_max3_f32 v10, v10, |v28|, |v29|
	v_max3_f32 v10, v10, |v30|, |v31|
	v_add_u32_e32 v8, 0x1000, v8
	global_load_dword v16, v8, s[42:43]
	global_load_dword v17, v8, s[42:43] offset:256
	global_load_dword v18, v8, s[42:43] offset:512
	global_load_dword v19, v8, s[42:43] offset:768
	global_load_dword v20, v8, s[42:43] offset:1024
	global_load_dword v21, v8, s[42:43] offset:1280
	global_load_dword v22, v8, s[42:43] offset:1536
	global_load_dword v23, v8, s[42:43] offset:1792
	global_load_dword v24, v8, s[42:43] offset:2048
	global_load_dword v25, v8, s[42:43] offset:2304
	global_load_dword v26, v8, s[42:43] offset:2560
	global_load_dword v27, v8, s[42:43] offset:2816
	global_load_dword v28, v8, s[42:43] offset:3072
	global_load_dword v29, v8, s[42:43] offset:3328
	global_load_dword v30, v8, s[42:43] offset:3584
	global_load_dword v31, v8, s[42:43] offset:3840
	s_waitcnt vmcnt(0)
	v_max3_f32 v10, v10, |v16|, |v17|
	v_max3_f32 v10, v10, |v18|, |v19|
	v_max3_f32 v10, v10, |v20|, |v21|
	v_max3_f32 v10, v10, |v22|, |v23|
	v_max3_f32 v10, v10, |v24|, |v25|
	v_max3_f32 v10, v10, |v26|, |v27|
	v_max3_f32 v10, v10, |v28|, |v29|
	v_max3_f32 v10, v10, |v30|, |v31|
	v_add_u32_e32 v8, 0x1000, v8
	global_load_dword v16, v8, s[42:43]
	global_load_dword v17, v8, s[42:43] offset:256
	global_load_dword v18, v8, s[42:43] offset:512
	global_load_dword v19, v8, s[42:43] offset:768
	global_load_dword v20, v8, s[42:43] offset:1024
	global_load_dword v21, v8, s[42:43] offset:1280
	global_load_dword v22, v8, s[42:43] offset:1536
	global_load_dword v23, v8, s[42:43] offset:1792
	global_load_dword v24, v8, s[42:43] offset:2048
	global_load_dword v25, v8, s[42:43] offset:2304
	global_load_dword v26, v8, s[42:43] offset:2560
	global_load_dword v27, v8, s[42:43] offset:2816
	global_load_dword v28, v8, s[42:43] offset:3072
	global_load_dword v29, v8, s[42:43] offset:3328
	global_load_dword v30, v8, s[42:43] offset:3584
	global_load_dword v31, v8, s[42:43] offset:3840
	s_waitcnt vmcnt(0)
	v_max3_f32 v10, v10, |v16|, |v17|
	v_max3_f32 v10, v10, |v18|, |v19|
	v_max3_f32 v10, v10, |v20|, |v21|
	v_max3_f32 v10, v10, |v22|, |v23|
	v_max3_f32 v10, v10, |v24|, |v25|
	v_max3_f32 v10, v10, |v26|, |v27|
	v_max3_f32 v10, v10, |v28|, |v29|
	v_max3_f32 v10, v10, |v30|, |v31|
	v_add_u32_e32 v8, 0x1000, v8
	global_load_dword v16, v8, s[42:43]
	global_load_dword v17, v8, s[42:43] offset:256
	global_load_dword v18, v8, s[42:43] offset:512
	global_load_dword v19, v8, s[42:43] offset:768
	global_load_dword v20, v8, s[42:43] offset:1024
	global_load_dword v21, v8, s[42:43] offset:1280
	global_load_dword v22, v8, s[42:43] offset:1536
	global_load_dword v23, v8, s[42:43] offset:1792
	global_load_dword v24, v8, s[42:43] offset:2048
	global_load_dword v25, v8, s[42:43] offset:2304
	v_mov_b32_e32 v26, 0
	v_cmp_gt_u32_e32 vcc, 8, v128
	s_and_saveexec_b64 s[4:5], vcc
	global_load_dword v26, v8, s[42:43] offset:2560
	s_or_b64 exec, exec, s[4:5]
	s_waitcnt vmcnt(0)
	v_max3_f32 v10, v10, |v16|, |v17|
	v_max3_f32 v10, v10, |v18|, |v19|
	v_max3_f32 v10, v10, |v20|, |v21|
	v_max3_f32 v10, v10, |v22|, |v23|
	v_max3_f32 v10, v10, |v24|, |v25|
	v_max_f32_e64 v11, |v26|, |v26|
	v_max_f32_e32 v10, v10, v11
